# EpiUp: tap-word wait relaxed to vmcnt(16) (only the tap load must be back, not the next unit's staged tiles)
# speedup vs baseline: 1.0339x; 1.0034x over previous
.LBB0_684:
	v_lshlrev_b32_e32 v132, 4, v206
	v_add3_u32 v133, s87, v157, v132
	v_lshlrev_b32_e32 v133, 3, v133
	v_add_u32_e32 v133, 0x22800, v133
	s_lshl_b32 s10, s16, 10
	s_lshl_b32 s11, s79, 2
	s_add_i32 s10, s10, s11
	s_add_i32 s10, s10, 0x23800
	v_lshl_add_u32 v154, v157, 4, s10
	ds_read_b128 v[150:153], v154
	ds_read_b128 v[158:161], v154 offset:512
	s_waitcnt vmcnt(16)
	ds_write_b64 v133, v[182:183]
	v_add_u32_e32 v155, s92, v132
	v_lshlrev_b32_e32 v204, 5, v206
	s_lshl_b32 s11, s84, 2
	s_add_i32 s11, s11, 0x22800
	v_add_u32_e32 v204, s11, v204
	v_add_u32_e32 v205, 0xfffff800, v155
	v_lshlrev_b32_e32 v221, 9, v157
	v_add_u32_e32 v221, v221, v132
	v_lshlrev_b32_e32 v3, 5, v206
	v_cmp_eq_u32_e64 s[56:57], 15, v157
	s_mul_i32 s14, s48, 0x160000
	s_lshl_b32 s15, s19, 9
	s_add_i32 s14, s14, s15
	s_lshr_b32 s15, s84, 6
	s_lshl_b32 s15, s15, 15
	s_add_i32 s14, s14, s15
	s_lshl_b32 s15, s79, 7
	s_add_i32 s14, s14, s15
	s_and_b32 s15, s84, 32
	s_lshl_b32 s15, s15, 1
	s_add_i32 s14, s14, s15
	s_add_u32 s14, s20, s14
	s_addc_u32 s15, s21, 0
	s_add_u32 s50, s14, 0x4000
	s_addc_u32 s51, s15, 0
	s_mul_i32 s41, s48, 0xb000
	s_lshl_b32 s49, s19, 3
	s_add_i32 s41, s41, s49
	s_lshl_b32 s49, s84, 2
	s_add_i32 s41, s41, s49
	s_mov_b32 s10, 0xbfb8aa3b
	s_mov_b32 s11, 0xbfb8aa3b
	s_mov_b32 s12, 1.0
	s_mov_b32 s13, 1.0
	s_waitcnt lgkmcnt(0)
	v_pk_mul_f32 v[120:121], v[120:121], v[152:153] op_sel_hi:[1,0]
	v_pk_mul_f32 v[122:123], v[122:123], v[152:153] op_sel_hi:[1,0]
	v_pk_mul_f32 v[116:117], v[116:117], v[152:153] op_sel:[0,1]
	v_pk_mul_f32 v[118:119], v[118:119], v[152:153] op_sel:[0,1]
	v_pk_mul_f32 v[104:105], v[104:105], v[152:153] op_sel_hi:[1,0]
	v_pk_mul_f32 v[106:107], v[106:107], v[152:153] op_sel_hi:[1,0]
	v_pk_mul_f32 v[100:101], v[100:101], v[152:153] op_sel:[0,1]
	v_pk_mul_f32 v[102:103], v[102:103], v[152:153] op_sel:[0,1]
	v_pk_mul_f32 v[88:89], v[88:89], v[152:153] op_sel_hi:[1,0]
	v_pk_mul_f32 v[90:91], v[90:91], v[152:153] op_sel_hi:[1,0]
	v_pk_mul_f32 v[84:85], v[84:85], v[152:153] op_sel:[0,1]
	v_pk_mul_f32 v[86:87], v[86:87], v[152:153] op_sel:[0,1]
	v_pk_mul_f32 v[72:73], v[72:73], v[152:153] op_sel_hi:[1,0]
	v_pk_mul_f32 v[74:75], v[74:75], v[152:153] op_sel_hi:[1,0]
	v_pk_mul_f32 v[68:69], v[68:69], v[152:153] op_sel:[0,1]
	v_pk_mul_f32 v[70:71], v[70:71], v[152:153] op_sel:[0,1]
	v_pk_mul_f32 v[56:57], v[56:57], v[160:161] op_sel_hi:[1,0]
	v_pk_mul_f32 v[58:59], v[58:59], v[160:161] op_sel_hi:[1,0]
	v_pk_mul_f32 v[52:53], v[52:53], v[160:161] op_sel:[0,1]
	v_pk_mul_f32 v[54:55], v[54:55], v[160:161] op_sel:[0,1]
	v_pk_mul_f32 v[40:41], v[40:41], v[160:161] op_sel_hi:[1,0]
	v_pk_mul_f32 v[42:43], v[42:43], v[160:161] op_sel_hi:[1,0]
	v_pk_mul_f32 v[36:37], v[36:37], v[160:161] op_sel:[0,1]
	v_pk_mul_f32 v[38:39], v[38:39], v[160:161] op_sel:[0,1]
	v_pk_mul_f32 v[24:25], v[24:25], v[160:161] op_sel_hi:[1,0]
	v_pk_mul_f32 v[26:27], v[26:27], v[160:161] op_sel_hi:[1,0]
	v_pk_mul_f32 v[20:21], v[20:21], v[160:161] op_sel:[0,1]
	v_pk_mul_f32 v[22:23], v[22:23], v[160:161] op_sel:[0,1]
	v_pk_mul_f32 v[8:9], v[8:9], v[160:161] op_sel_hi:[1,0]
	v_pk_mul_f32 v[10:11], v[10:11], v[160:161] op_sel_hi:[1,0]
	v_pk_mul_f32 v[4:5], v[4:5], v[160:161] op_sel:[0,1]
	v_pk_mul_f32 v[6:7], v[6:7], v[160:161] op_sel:[0,1]
	s_and_saveexec_b64 s[52:53], s[56:57]
	ds_write_b128 v155, v[120:123] offset:0
	ds_write_b128 v155, v[116:119] offset:256
	ds_write_b128 v155, v[88:91] offset:64
	ds_write_b128 v155, v[84:87] offset:320
	ds_write_b128 v155, v[104:107] offset:128
	ds_write_b128 v155, v[100:103] offset:384
	ds_write_b128 v155, v[72:75] offset:192
	ds_write_b128 v155, v[68:71] offset:448
	ds_write_b128 v155, v[56:59] offset:4096
	ds_write_b128 v155, v[52:55] offset:4352
	ds_write_b128 v155, v[24:27] offset:4160
	ds_write_b128 v155, v[20:23] offset:4416
	ds_write_b128 v155, v[40:43] offset:4224
	ds_write_b128 v155, v[36:39] offset:4480
	ds_write_b128 v155, v[8:11] offset:4288
	ds_write_b128 v155, v[4:7] offset:4544
	s_mov_b64 exec, s[52:53]
	v_pk_mul_f32 v[128:129], v[128:129], v[150:151] op_sel_hi:[1,0]
	v_pk_mul_f32 v[130:131], v[130:131], v[150:151] op_sel_hi:[1,0]
	v_pk_mul_f32 v[124:125], v[124:125], v[150:151] op_sel:[0,1]
	v_pk_mul_f32 v[126:127], v[126:127], v[150:151] op_sel:[0,1]
	v_pk_mul_f32 v[112:113], v[112:113], v[150:151] op_sel_hi:[1,0]
	v_pk_mul_f32 v[114:115], v[114:115], v[150:151] op_sel_hi:[1,0]
	v_pk_mul_f32 v[108:109], v[108:109], v[150:151] op_sel:[0,1]
	v_pk_mul_f32 v[110:111], v[110:111], v[150:151] op_sel:[0,1]
	v_pk_mul_f32 v[96:97], v[96:97], v[150:151] op_sel_hi:[1,0]
	v_pk_mul_f32 v[98:99], v[98:99], v[150:151] op_sel_hi:[1,0]
	v_pk_mul_f32 v[92:93], v[92:93], v[150:151] op_sel:[0,1]
	v_pk_mul_f32 v[94:95], v[94:95], v[150:151] op_sel:[0,1]
	v_pk_mul_f32 v[80:81], v[80:81], v[150:151] op_sel_hi:[1,0]
	v_pk_mul_f32 v[82:83], v[82:83], v[150:151] op_sel_hi:[1,0]
	v_pk_mul_f32 v[76:77], v[76:77], v[150:151] op_sel:[0,1]
	v_pk_mul_f32 v[78:79], v[78:79], v[150:151] op_sel:[0,1]
	v_pk_mul_f32 v[64:65], v[64:65], v[158:159] op_sel_hi:[1,0]
	v_pk_mul_f32 v[66:67], v[66:67], v[158:159] op_sel_hi:[1,0]
	v_pk_mul_f32 v[60:61], v[60:61], v[158:159] op_sel:[0,1]
	v_pk_mul_f32 v[62:63], v[62:63], v[158:159] op_sel:[0,1]
	v_pk_mul_f32 v[48:49], v[48:49], v[158:159] op_sel_hi:[1,0]
	v_pk_mul_f32 v[50:51], v[50:51], v[158:159] op_sel_hi:[1,0]
	v_pk_mul_f32 v[44:45], v[44:45], v[158:159] op_sel:[0,1]
	v_pk_mul_f32 v[46:47], v[46:47], v[158:159] op_sel:[0,1]
	v_pk_mul_f32 v[32:33], v[32:33], v[158:159] op_sel_hi:[1,0]
	v_pk_mul_f32 v[34:35], v[34:35], v[158:159] op_sel_hi:[1,0]
	v_pk_mul_f32 v[28:29], v[28:29], v[158:159] op_sel:[0,1]
	v_pk_mul_f32 v[30:31], v[30:31], v[158:159] op_sel:[0,1]
	v_pk_mul_f32 v[16:17], v[16:17], v[158:159] op_sel_hi:[1,0]
	v_pk_mul_f32 v[18:19], v[18:19], v[158:159] op_sel_hi:[1,0]
	v_pk_mul_f32 v[12:13], v[12:13], v[158:159] op_sel:[0,1]
	v_pk_mul_f32 v[14:15], v[14:15], v[158:159] op_sel:[0,1]
	s_waitcnt lgkmcnt(0)
	s_barrier
	ds_read_b128 v[134:137], v204 offset:0
	ds_read_b128 v[138:141], v204 offset:1024
	ds_read_b128 v[142:145], v204 offset:2048
	ds_read_b128 v[146:149], v204 offset:3072
	ds_read_b128 v[222:225], v205 offset:0
	ds_read_b128 v[226:229], v205 offset:256
	ds_read_b128 v[230:233], v205 offset:4096
	ds_read_b128 v[234:237], v205 offset:4352
	ds_read_b128 v[184:187], v204 offset:512
	ds_read_b128 v[188:191], v204 offset:1536
	ds_read_b128 v[192:195], v204 offset:2560
	ds_read_b128 v[196:199], v204 offset:3584
	s_waitcnt lgkmcnt(6)
	s_and_b64 vcc, exec, s[28:29]
	s_cbranch_vccz .Lup_z000
	v_mov_b32_dpp v226, v116 row_shr:1 row_mask:0xf bank_mask:0xf
	v_mov_b32_dpp v227, v117 row_shr:1 row_mask:0xf bank_mask:0xf
	v_mov_b32_dpp v228, v118 row_shr:1 row_mask:0xf bank_mask:0xf
	v_mov_b32_dpp v229, v119 row_shr:1 row_mask:0xf bank_mask:0xf
	v_mov_b32_dpp v222, v120 row_shr:1 row_mask:0xf bank_mask:0xf
	v_mov_b32_dpp v223, v121 row_shr:1 row_mask:0xf bank_mask:0xf
	v_mov_b32_dpp v224, v122 row_shr:1 row_mask:0xf bank_mask:0xf
	v_mov_b32_dpp v225, v123 row_shr:1 row_mask:0xf bank_mask:0xf
	s_branch .Lup_d000
